# v026 stack + warm-up loads of the FFN-up epilogue row statistics issued in the unit's last K-loop iteration
# baseline (speedup 1.0000x reference)
.LBB0_2836:
	s_cmp_lg_u32 s75, 14
	s_cbranch_scc1 .Lffn1_pf_skip
	s_cmp_eq_u32 s68, 64
	s_cbranch_scc1 .Lffn1_pf_skip
	v_readfirstlane_b32 s100, v0
	s_ashr_i32 s100, s100, 2
	s_andn2_b32 s100, s100, 63
	v_and_or_b32 v216, v0, 15, s100
	v_lshl_add_u32 v216, s68, 8, v216
	v_ashrrev_i32_e32 v217, 31, v216
	v_lshl_add_u64 v[216:217], v[216:217], 2, s[22:23]
	global_load_dword v218, v[216:217], off
	global_load_dword v219, v[216:217], off offset:128
	global_load_dword v220, v[216:217], off offset:512
	global_load_dword v221, v[216:217], off offset:640
